# attention pass 0: overlapping half of K/V window kept in registers across consecutive items instead of reloaded; plus hand-written P0
# baseline (speedup 1.0000x reference)
; #define LAS __attribute__((address_space(3)))
;     ...
;     int item = SB ? 0 : (int)blockIdx.x; const int item_end = SB ? 4 : 3072, item_step = SB ? 1 : G;
;     const bool hoist = SB || (G & 15) == 0;
;     if (hoist && tid < 200) { const int bi = tid - 32; bias[tid] = (bi >= 0 && bi <= 128) ? rel_bias[t5_bucket((bi - 64) * D) * 16 + (SB ? sb_h : (item & 15))] * LOG2E : -1.0e30f; }
;     if (item < item_end) { ATT_DECODE(item) ATT_LOAD(); }
;     for (; item < item_end; item += item_step) {
;         ATT_DECODE(item)
; #pragma unroll
;         for (int i = 0; i < 8; ++i) { const int r = r0 + 32 * i;
;             *(LAS u32x4*)(lds + KOFF + r * PITCH + ch * 16) = kv[i]; *(LAS u32x4*)(lds + VOFF + r * VPITCH + ch * 16) = vv[i]; }
;         if (!hoist) { if (tid < 200) { const int bi = tid - 32; bias[tid] = (bi >= 0 && bi <= 128) ? rel_bias[t5_bucket((bi - 64) * D) * 16 + h] * LOG2E : -1.0e30f; } }
;         bf16x8 qf[4];
; #pragma unroll
;         for (int kk = 0; kk < 4; ++kk) qf[kk] = qn[kk];
;         const int qrow = seq_base + (qb * 128 + 16 * w + fr) * D + g;
;         asm volatile("s_waitcnt lgkmcnt(0)\n\ts_barrier" ::: "memory");
;         if (item + item_step < item_end) { const int nit = item + item_step; ATT_DECODE(nit) ATT_LOAD(); }
;         const int ts = w & ~1;
.LBB0_169:
	v_add_u32_e32 v0, s23, v222
	v_add_u32_e32 v1, 64, v0
	v_min_i32_e32 v1, s22, v1
	s_waitcnt vmcnt(19)
	ds_write_b128 v216, v[8:11]
	s_waitcnt vmcnt(18)
	ds_write_b128 v217, v[4:7]
	s_waitcnt vmcnt(17)
	ds_write_b128 v216, v[28:31] offset:8704
	s_waitcnt vmcnt(16)
	ds_write_b128 v217, v[24:27] offset:9216
	s_waitcnt vmcnt(15)
	ds_write_b128 v216, v[36:39] offset:17408
	s_waitcnt vmcnt(14)
	ds_write_b128 v217, v[32:35] offset:18432
	s_waitcnt vmcnt(13)
	ds_write_b128 v216, v[44:47] offset:26112
	s_waitcnt vmcnt(12)
	ds_write_b128 v217, v[40:43] offset:27648
	s_waitcnt vmcnt(11)
	ds_write_b128 v216, v[52:55] offset:34816
	s_waitcnt vmcnt(10)
	ds_write_b128 v217, v[48:51] offset:36864
	s_waitcnt vmcnt(9)
	ds_write_b128 v216, v[60:63] offset:43520
	s_waitcnt vmcnt(8)
	ds_write_b128 v217, v[56:59] offset:46080
	s_waitcnt vmcnt(7)
	ds_write_b128 v216, v[68:71] offset:52224
	s_waitcnt vmcnt(6)
	ds_write_b128 v217, v[64:67] offset:55296
	s_waitcnt vmcnt(5)
	ds_write_b128 v216, v[76:79] offset:60928
	s_waitcnt vmcnt(4)
	ds_write_b128 v217, v[72:75] offset:64512
	v_add_u32_e32 v1, s15, v1
	s_waitcnt lgkmcnt(0)
	s_barrier
	v_mov_b64_e32 v[8:9], v[52:53]
	v_mov_b64_e32 v[10:11], v[54:55]
	v_mov_b64_e32 v[28:29], v[60:61]
	v_mov_b64_e32 v[30:31], v[62:63]
	v_mov_b64_e32 v[36:37], v[68:69]
	v_mov_b64_e32 v[38:39], v[70:71]
	v_mov_b64_e32 v[44:45], v[76:77]
	v_mov_b64_e32 v[46:47], v[78:79]
	v_mov_b64_e32 v[4:5], v[48:49]
	v_mov_b64_e32 v[6:7], v[50:51]
	v_mov_b64_e32 v[24:25], v[56:57]
	v_mov_b64_e32 v[26:27], v[58:59]
	v_mov_b64_e32 v[32:33], v[64:65]
	v_mov_b64_e32 v[34:35], v[66:67]
	v_mov_b64_e32 v[40:41], v[72:73]
	v_mov_b64_e32 v[42:43], v[74:75]
	v_lshl_or_b32 v1, v1, 8, v173
	v_add_u32_e32 v1, 0x60, v0
	v_min_i32_e32 v1, s22, v1
	v_add_u32_e32 v1, s15, v1
	v_lshl_or_b32 v1, v1, 8, v173
	v_add_u32_e32 v1, 0x80, v0
	v_min_i32_e32 v1, s22, v1
	v_add_u32_e32 v1, s15, v1
	v_lshl_or_b32 v1, v1, 8, v173
	v_add_u32_e32 v1, 0xa0, v0
	v_min_i32_e32 v1, s22, v1
	v_add_u32_e32 v1, s15, v1
	v_lshl_or_b32 v1, v1, 8, v173
	v_add_u32_e32 v1, 0xc0, v0
	v_min_i32_e32 v1, s22, v1
	v_add_u32_e32 v1, s15, v1
	v_lshl_or_b32 v1, v1, 8, v173
	global_load_dwordx4 v[52:55], v1, s[4:5]
	global_load_dwordx4 v[48:51], v1, s[2:3]
	v_add_u32_e32 v1, 0xe0, v0
	v_min_i32_e32 v1, s22, v1
	v_add_u32_e32 v1, s15, v1
	v_lshl_or_b32 v1, v1, 8, v173
	global_load_dwordx4 v[60:63], v1, s[4:5]
	global_load_dwordx4 v[56:59], v1, s[2:3]
	v_add_u32_e32 v1, 0x100, v0
	v_add_u32_e32 v0, 0x120, v0
	v_min_i32_e32 v1, s22, v1
	v_min_i32_e32 v0, s22, v0
	v_add_u32_e32 v1, s15, v1
	v_add_u32_e32 v0, s15, v0
	v_lshl_or_b32 v1, v1, 8, v173
	v_lshl_or_b32 v0, v0, 8, v173
	global_load_dwordx4 v[68:71], v1, s[4:5]
	global_load_dwordx4 v[64:67], v1, s[2:3]
	global_load_dwordx4 v[76:79], v0, s[4:5]
	global_load_dwordx4 v[72:75], v0, s[2:3]
	global_load_dwordx4 v[12:15], v189, s[94:95]
	global_load_dwordx4 v[16:19], v189, s[94:95] offset:64
	global_load_dwordx4 v[20:23], v189, s[94:95] offset:128
	s_nop 0
	global_load_dwordx4 v[0:3], v189, s[94:95] offset:192
	ds_read_b128 v[148:151], v190
	ds_read_b128 v[144:147], v190 offset:64
	ds_read_b128 v[140:143], v190 offset:128
	ds_read_b128 v[136:139], v190 offset:192
	ds_read_b128 v[164:167], v190 offset:4352
	ds_read_b128 v[160:163], v190 offset:4416
	ds_read_b128 v[156:159], v190 offset:4480
	ds_read_b128 v[152:155], v190 offset:4544
	ds_read_b128 v[96:99], v190 offset:8704
	ds_read_b128 v[92:95], v190 offset:8768
	ds_read_b128 v[84:87], v190 offset:8832
	ds_read_b128 v[80:83], v190 offset:8896
	ds_read_b128 v[116:119], v190 offset:13056
	ds_read_b128 v[112:115], v190 offset:13120
	ds_read_b128 v[104:107], v190 offset:13184
	ds_read_b128 v[100:103], v190 offset:13248
	s_mov_b64 s[0:1], -1
	s_and_b64 vcc, exec, s[12:13]
	s_cbranch_vccz .LBB0_171
	s_waitcnt vmcnt(15) lgkmcnt(11)
	v_mfma_f32_16x16x32_bf16 v[88:91], v[164:167], v[132:135], 0
	s_mov_b64 s[0:1], 0
	s_waitcnt vmcnt(14) lgkmcnt(10)
	v_mfma_f32_16x16x32_bf16 v[88:91], v[160:163], v[128:131], v[88:91]
	s_waitcnt vmcnt(13) lgkmcnt(9)
	v_mfma_f32_16x16x32_bf16 v[88:91], v[156:159], v[124:127], v[88:91]
	s_waitcnt vmcnt(12) lgkmcnt(8)
	v_mfma_f32_16x16x32_bf16 v[88:91], v[152:155], v[120:123], v[88:91]
; #define LAS __attribute__((address_space(3)))
; #define ATT_LDK(BUF, TP) _Pragma("unroll") for (int u = 0; u < 2; ++u) _Pragma("unroll") for (int kk = 0; kk < 4; ++kk) kf[BUF][u][kk] = *(const LAS bf16x8*)(kptr + (16 * (2 * (TP) + u)) * PITCH + kk * 64);
;     ...
;         {
;             LAS const unsigned char* kptr = lds + KOFF + (16 * ts + fr) * PITCH + fq * 16;
;             bf16x8 kf[2][2][4];
;     ...
;             ATT_LDK(0, 0)
; #pragma unroll
;             for (int tp = 0; tp < 5; ++tp) {
;                 if (tp + 1 < 5) { ATT_LDK((tp + 1) & 1, tp + 1) }
;                 __builtin_amdgcn_sched_barrier(0);
;                 s[2 * tp] = (f32x4){0.f, 0.f, 0.f, 0.f}; s[2 * tp + 1] = (f32x4){0.f, 0.f, 0.f, 0.f};
;                 if (tp == 0 && (w & 1)) {
; #pragma unroll
;                     for (int kk = 0; kk < 4; ++kk) s[1] = __builtin_amdgcn_mfma_f32_16x16x32_bf16(kf[0][1][kk], qf[kk], s[1], 0, 0, 0);
;                 } else if (tp == 4 && !(w & 1)) {
; #pragma unroll
;                     for (int kk = 0; kk < 4; ++kk) s[8] = __builtin_amdgcn_mfma_f32_16x16x32_bf16(kf[0][0][kk], qf[kk], s[8], 0, 0, 0);
;                 } else {
; #pragma unroll
;                 for (int kk = 0; kk < 4; ++kk) { s[2 * tp] = __builtin_amdgcn_mfma_f32_16x16x32_bf16(kf[tp & 1][0][kk], qf[kk], s[2 * tp], 0, 0, 0);
;                     s[2 * tp + 1] = __builtin_amdgcn_mfma_f32_16x16x32_bf16(kf[tp & 1][1][kk], qf[kk], s[2 * tp + 1], 0, 0, 0); } }
;                 __builtin_amdgcn_sched_barrier(0);
;             }
;     ...
;         }
.LBB0_171:
	v_mov_b32_e32 v108, 0
	s_andn2_b64 vcc, exec, s[0:1]
	v_mov_b32_e32 v109, 0
	v_mov_b32_e32 v110, 0
	v_mov_b32_e32 v111, 0
	s_cbranch_vccnz .LBB0_173
	s_waitcnt vmcnt(15) lgkmcnt(14)
	v_mfma_f32_16x16x32_bf16 v[88:91], v[148:151], v[132:135], 0
	s_waitcnt lgkmcnt(11)
	v_mfma_f32_16x16x32_bf16 v[108:111], v[164:167], v[132:135], 0
	s_waitcnt vmcnt(14)
	v_mfma_f32_16x16x32_bf16 v[88:91], v[144:147], v[128:131], v[88:91]
	s_waitcnt lgkmcnt(10)
	v_mfma_f32_16x16x32_bf16 v[108:111], v[160:163], v[128:131], v[108:111]
	s_waitcnt vmcnt(13)
	v_mfma_f32_16x16x32_bf16 v[88:91], v[140:143], v[124:127], v[88:91]
	s_waitcnt lgkmcnt(9)
	v_mfma_f32_16x16x32_bf16 v[140:143], v[156:159], v[124:127], v[108:111]
	s_waitcnt vmcnt(12)
	v_mfma_f32_16x16x32_bf16 v[108:111], v[136:139], v[120:123], v[88:91]
	s_waitcnt lgkmcnt(8)
	v_mfma_f32_16x16x32_bf16 v[88:91], v[152:155], v[120:123], v[140:143]
.LBB0_173:
	s_waitcnt lgkmcnt(12)
	ds_read_b128 v[136:139], v190 offset:17408
	s_nop 1
	ds_read_b128 v[140:143], v190 offset:17472
	ds_read_b128 v[144:147], v190 offset:17536
	ds_read_b128 v[148:151], v190 offset:17600
	s_waitcnt lgkmcnt(12)
	ds_read_b128 v[152:155], v190 offset:21760
	ds_read_b128 v[156:159], v190 offset:21824
	ds_read_b128 v[160:163], v190 offset:21888
	ds_read_b128 v[164:167], v190 offset:21952
	s_waitcnt vmcnt(15) lgkmcnt(14)
	v_mfma_f32_16x16x32_bf16 v[96:99], v[96:99], v[132:135], 0
	s_waitcnt lgkmcnt(11)
	v_mfma_f32_16x16x32_bf16 v[116:119], v[116:119], v[132:135], 0
	s_waitcnt vmcnt(14)
	v_mfma_f32_16x16x32_bf16 v[92:95], v[92:95], v[128:131], v[96:99]
	s_waitcnt lgkmcnt(10)
	v_mfma_f32_16x16x32_bf16 v[96:99], v[112:115], v[128:131], v[116:119]
	s_waitcnt vmcnt(13)
	v_mfma_f32_16x16x32_bf16 v[84:87], v[84:87], v[124:127], v[92:95]
	s_waitcnt lgkmcnt(9)
	v_mfma_f32_16x16x32_bf16 v[92:95], v[104:107], v[124:127], v[96:99]
	s_waitcnt vmcnt(12)
	v_mfma_f32_16x16x32_bf16 v[116:119], v[80:83], v[120:123], v[84:87]
	s_waitcnt lgkmcnt(8)
	v_mfma_f32_16x16x32_bf16 v[112:115], v[100:103], v[120:123], v[92:95]
	ds_read_b128 v[80:83], v190 offset:26112
	s_nop 0
	ds_read_b128 v[84:87], v190 offset:26176
	s_nop 0
	ds_read_b128 v[92:95], v190 offset:26240
	ds_read_b128 v[96:99], v190 offset:26304
	ds_read_b128 v[228:231], v190 offset:30464
	ds_read_b128 v[232:235], v190 offset:30528
	ds_read_b128 v[236:239], v190 offset:30592
	ds_read_b128 v[240:243], v190 offset:30656
	s_waitcnt lgkmcnt(14)
	v_mfma_f32_16x16x32_bf16 v[100:103], v[136:139], v[132:135], 0
	s_waitcnt lgkmcnt(11)
	v_mfma_f32_16x16x32_bf16 v[104:107], v[152:155], v[132:135], 0
	v_mfma_f32_16x16x32_bf16 v[100:103], v[140:143], v[128:131], v[100:103]
	s_waitcnt lgkmcnt(10)
	v_mfma_f32_16x16x32_bf16 v[104:107], v[156:159], v[128:131], v[104:107]
	v_mfma_f32_16x16x32_bf16 v[100:103], v[144:147], v[124:127], v[100:103]
	s_waitcnt lgkmcnt(9)
	v_mfma_f32_16x16x32_bf16 v[136:139], v[160:163], v[124:127], v[104:107]
	v_mfma_f32_16x16x32_bf16 v[104:107], v[148:151], v[120:123], v[100:103]
	s_waitcnt lgkmcnt(8)
	v_mfma_f32_16x16x32_bf16 v[100:103], v[164:167], v[120:123], v[136:139]
	ds_read_b128 v[140:143], v190 offset:34816
	ds_read_b128 v[144:147], v190 offset:34880
	ds_read_b128 v[148:151], v190 offset:34944
	s_nop 1
	ds_read_b128 v[136:139], v190 offset:35008
	ds_read_b128 v[164:167], v190 offset:39168
	ds_read_b128 v[160:163], v190 offset:39232
	ds_read_b128 v[156:159], v190 offset:39296
	ds_read_b128 v[152:155], v190 offset:39360
	s_waitcnt lgkmcnt(14)
	v_mfma_f32_16x16x32_bf16 v[80:83], v[80:83], v[132:135], 0
	s_waitcnt lgkmcnt(11)
	v_mfma_f32_16x16x32_bf16 v[228:231], v[228:231], v[132:135], 0
	v_mfma_f32_16x16x32_bf16 v[80:83], v[84:87], v[128:131], v[80:83]
	s_waitcnt lgkmcnt(10)
	v_mfma_f32_16x16x32_bf16 v[84:87], v[232:235], v[128:131], v[228:231]
	v_mfma_f32_16x16x32_bf16 v[80:83], v[92:95], v[124:127], v[80:83]
	s_waitcnt lgkmcnt(9)
	v_mfma_f32_16x16x32_bf16 v[84:87], v[236:239], v[124:127], v[84:87]
	v_mfma_f32_16x16x32_bf16 v[96:99], v[96:99], v[120:123], v[80:83]
	s_waitcnt lgkmcnt(8)
	v_mfma_f32_16x16x32_bf16 v[84:87], v[240:243], v[120:123], v[84:87]
	s_nop 2
	v_cndmask_b32_e64 v80, 0, 1, s[12:13]
	v_cmp_ne_u32_e64 s[8:9], 1, v80
	s_andn2_b64 vcc, exec, s[12:13]
	s_mov_b64 s[0:1], -1
	s_cbranch_vccnz .LBB0_175
	s_waitcnt lgkmcnt(7)
	v_mfma_f32_16x16x32_bf16 v[80:83], v[140:143], v[132:135], 0
	s_mov_b64 s[0:1], 0
	s_waitcnt lgkmcnt(3)
	v_mfma_f32_16x16x32_bf16 v[92:95], v[164:167], v[132:135], 0
	v_mfma_f32_16x16x32_bf16 v[80:83], v[144:147], v[128:131], v[80:83]
	s_waitcnt lgkmcnt(2)
	v_mfma_f32_16x16x32_bf16 v[92:95], v[160:163], v[128:131], v[92:95]
	v_mfma_f32_16x16x32_bf16 v[80:83], v[148:151], v[124:127], v[80:83]
	s_waitcnt lgkmcnt(1)
	v_mfma_f32_16x16x32_bf16 v[156:159], v[156:159], v[124:127], v[92:95]
	v_mfma_f32_16x16x32_bf16 v[92:95], v[136:139], v[120:123], v[80:83]
	s_waitcnt lgkmcnt(0)
	v_mfma_f32_16x16x32_bf16 v[80:83], v[152:155], v[120:123], v[156:159]
